# v26 + latent attention K/V DMA issue block moved from tile head into the QK result wait
# baseline (speedup 1.0000x reference)
.LBB0_781:
	s_waitcnt vmcnt(8)
	s_waitcnt lgkmcnt(0)
	s_barrier
	s_and_b32 s5, s4, 0x18000
	s_add_i32 s5, s5, 0
	v_add_u32_e32 v48, s5, v190
	v_add_u32_e32 v49, v48, v191
	v_add_u32_e32 v51, v48, v193
	v_add_u32_e32 v50, v48, v192
	ds_read_b128 v[66:69], v49
	ds_read_b128 v[70:73], v50
	v_add_u32_e32 v230, v48, v194
	ds_read_b128 v[74:77], v51
	ds_read_b128 v[94:97], v230
	ds_read_b128 v[198:201], v49 offset:8192
	ds_read_b128 v[202:205], v50 offset:8192
	ds_read_b128 v[226:229], v51 offset:8192
	s_waitcnt lgkmcnt(6)
	s_nop 0
	v_mfma_f32_32x32x16_bf16 v[48:63], v[66:69], v[126:129], v[232:247]
	s_waitcnt lgkmcnt(5)
	v_mfma_f32_32x32x16_bf16 v[48:63], v[70:73], v[130:133], v[48:63]
	ds_read_b128 v[70:73], v230 offset:8192
	s_waitcnt lgkmcnt(5)
	v_mfma_f32_32x32x16_bf16 v[48:63], v[74:77], v[134:137], v[48:63]
	s_waitcnt lgkmcnt(4)
	v_mfma_f32_32x32x16_bf16 v[48:63], v[94:97], v[138:141], v[48:63]
	s_nop 7
	s_nop 3
	v_max_f32_e32 v65, v49, v49
	v_max_f32_e32 v66, v48, v48
	s_waitcnt lgkmcnt(3)
	v_mfma_f32_32x32x16_bf16 v[94:109], v[198:201], v[126:129], v[232:247]
	v_max_f32_e32 v65, v66, v65
	v_max3_f32 v65, v65, v50, v51
	v_max3_f32 v65, v65, v52, v53
	v_max3_f32 v65, v65, v54, v55
	v_max3_f32 v65, v65, v56, v57
	v_max3_f32 v65, v65, v58, v59
	v_max3_f32 v65, v65, v60, v61
	s_waitcnt lgkmcnt(2)
	v_mfma_f32_32x32x16_bf16 v[94:109], v[202:205], v[130:133], v[94:109]
	v_max3_f32 v65, v65, v62, v63
	v_add_f32_e32 v66, 0x41000000, v196
	s_waitcnt lgkmcnt(1)
	v_mfma_f32_32x32x16_bf16 v[94:109], v[226:229], v[134:137], v[94:109]
	s_waitcnt lgkmcnt(0)
	v_mfma_f32_32x32x16_bf16 v[94:109], v[70:73], v[138:141], v[94:109]
	s_add_i32 s5, s18, -3
	s_min_i32 s19, s18, 0x43
	s_cmp_lt_u32 s5, 61
	s_cselect_b64 s[20:21], -1, 0
	s_and_b64 s[40:41], s[20:21], exec
	s_cselect_b32 s5, 0, 0xffffffc0
	s_add_i32 s5, s5, s19
	s_and_b64 s[20:21], s[20:21], exec
	s_cselect_b32 s21, s8, s13
	s_cselect_b32 s20, s7, s11
	s_cselect_b32 s41, s10, s17
	s_cselect_b32 s40, s9, s16
	s_cselect_b32 s19, s64, 0x100
	s_lshl_b32 s5, s5, 6
	v_add_u32_e32 v116, s5, v181
	v_mov_b64_e32 v[112:113], s[20:21]
	s_add_i32 s33, s4, 0x18000
	v_mad_i64_i32 v[114:115], s[20:21], s19, v116, v[112:113]
	s_and_b32 s33, s33, 0x18000
	v_lshl_add_u64 v[110:111], s[40:41], 0, v[144:145]
	v_lshl_add_u64 v[114:115], v[114:115], 0, v[176:177]
	s_add_i32 s33, s33, s25
	s_mov_b32 s20, m0
	s_mov_b32 m0, s33
	s_nop 0
	global_load_lds_dwordx4 v[114:115], off
	s_mov_b32 m0, s20
	s_add_i32 s40, s33, 0x4000
	v_mad_i64_i32 v[114:115], s[20:21], s19, v116, v[110:111]
	s_mov_b32 s20, m0
	s_mov_b32 m0, s40
	s_nop 0
	global_load_lds_dwordx4 v[114:115], off
	s_mov_b32 m0, s20
	v_add_u32_e32 v114, s5, v182
	v_mad_i64_i32 v[112:113], s[20:21], s19, v114, v[112:113]
	v_lshl_add_u64 v[112:113], v[112:113], 0, v[178:179]
	s_add_i32 s5, s33, 0x400
	s_mov_b32 s20, m0
	s_mov_b32 m0, s5
	s_nop 0
	global_load_lds_dwordx4 v[112:113], off
	s_mov_b32 m0, s20
	s_addk_i32 s33, 0x4400
	v_mad_i64_i32 v[110:111], s[20:21], s19, v114, v[110:111]
	s_mov_b32 s5, m0
	s_mov_b32 m0, s33
	s_nop 0
	global_load_lds_dwordx4 v[110:111], off
	s_mov_b32 m0, s5
	s_and_b32 s5, s4, 0x18000
	v_max3_f32 v65, v65, v94, v95
	v_max3_f32 v65, v65, v96, v97
	v_max3_f32 v65, v65, v98, v99
	v_max3_f32 v65, v65, v100, v101
	v_max3_f32 v65, v65, v102, v103
	v_max3_f32 v65, v65, v104, v105
	v_max3_f32 v65, v65, v106, v107
	v_max3_f32 v65, v65, v108, v109
	v_sub_f32_e32 v65, v65, v232
	v_cmp_gt_f32_e32 vcc, v65, v66
	s_cbranch_vccz .LBB0_780
	ds_bpermute_b32 v66, v214, v65
	s_waitcnt lgkmcnt(0)
	v_max3_f32 v65, v196, v65, v66
	v_sub_f32_e32 v66, v196, v65
	v_exp_f32_e32 v66, v66
	v_add_f32_e32 v68, v232, v65
	v_pk_add_f32 v[48:49], v[48:49], v[68:69] op_sel_hi:[1,0] neg_lo:[0,1] neg_hi:[0,1]
	v_pk_add_f32 v[50:51], v[50:51], v[68:69] op_sel_hi:[1,0] neg_lo:[0,1] neg_hi:[0,1]
	v_pk_mul_f32 v[92:93], v[92:93], v[66:67] op_sel_hi:[1,0]
	v_pk_mul_f32 v[90:91], v[90:91], v[66:67] op_sel_hi:[1,0]
	v_pk_mul_f32 v[88:89], v[88:89], v[66:67] op_sel_hi:[1,0]
	v_pk_mul_f32 v[86:87], v[86:87], v[66:67] op_sel_hi:[1,0]
	v_pk_mul_f32 v[84:85], v[84:85], v[66:67] op_sel_hi:[1,0]
	v_pk_mul_f32 v[82:83], v[82:83], v[66:67] op_sel_hi:[1,0]
	v_pk_mul_f32 v[80:81], v[80:81], v[66:67] op_sel_hi:[1,0]
	v_pk_mul_f32 v[78:79], v[78:79], v[66:67] op_sel_hi:[1,0]
	v_pk_mul_f32 v[46:47], v[46:47], v[66:67] op_sel_hi:[1,0]
	v_pk_mul_f32 v[44:45], v[44:45], v[66:67] op_sel_hi:[1,0]
	v_pk_mul_f32 v[42:43], v[42:43], v[66:67] op_sel_hi:[1,0]
	v_pk_mul_f32 v[40:41], v[40:41], v[66:67] op_sel_hi:[1,0]
	v_pk_mul_f32 v[38:39], v[38:39], v[66:67] op_sel_hi:[1,0]
	v_pk_mul_f32 v[36:37], v[36:37], v[66:67] op_sel_hi:[1,0]
	v_pk_mul_f32 v[34:35], v[34:35], v[66:67] op_sel_hi:[1,0]
	v_pk_mul_f32 v[32:33], v[32:33], v[66:67] op_sel_hi:[1,0]
	v_pk_mul_f32 v[30:31], v[30:31], v[66:67] op_sel_hi:[1,0]
	v_pk_mul_f32 v[28:29], v[28:29], v[66:67] op_sel_hi:[1,0]
	v_pk_mul_f32 v[26:27], v[26:27], v[66:67] op_sel_hi:[1,0]
	v_pk_mul_f32 v[24:25], v[24:25], v[66:67] op_sel_hi:[1,0]
	v_pk_mul_f32 v[22:23], v[22:23], v[66:67] op_sel_hi:[1,0]
	v_pk_mul_f32 v[20:21], v[20:21], v[66:67] op_sel_hi:[1,0]
	v_pk_mul_f32 v[18:19], v[18:19], v[66:67] op_sel_hi:[1,0]
	v_pk_mul_f32 v[16:17], v[16:17], v[66:67] op_sel_hi:[1,0]
	v_pk_mul_f32 v[14:15], v[14:15], v[66:67] op_sel_hi:[1,0]
	v_pk_mul_f32 v[12:13], v[12:13], v[66:67] op_sel_hi:[1,0]
	v_pk_mul_f32 v[10:11], v[10:11], v[66:67] op_sel_hi:[1,0]
	v_pk_mul_f32 v[8:9], v[8:9], v[66:67] op_sel_hi:[1,0]
	v_pk_mul_f32 v[6:7], v[6:7], v[66:67] op_sel_hi:[1,0]
	v_pk_mul_f32 v[4:5], v[4:5], v[66:67] op_sel_hi:[1,0]
	v_pk_mul_f32 v[2:3], v[2:3], v[66:67] op_sel_hi:[1,0]
	v_pk_mul_f32 v[0:1], v[0:1], v[66:67] op_sel_hi:[1,0]
	v_pk_add_f32 v[52:53], v[52:53], v[68:69] op_sel_hi:[1,0] neg_lo:[0,1] neg_hi:[0,1]
	v_pk_add_f32 v[54:55], v[54:55], v[68:69] op_sel_hi:[1,0] neg_lo:[0,1] neg_hi:[0,1]
	v_pk_add_f32 v[56:57], v[56:57], v[68:69] op_sel_hi:[1,0] neg_lo:[0,1] neg_hi:[0,1]
	v_pk_add_f32 v[58:59], v[58:59], v[68:69] op_sel_hi:[1,0] neg_lo:[0,1] neg_hi:[0,1]
	v_pk_add_f32 v[60:61], v[60:61], v[68:69] op_sel_hi:[1,0] neg_lo:[0,1] neg_hi:[0,1]
	v_pk_add_f32 v[62:63], v[62:63], v[68:69] op_sel_hi:[1,0] neg_lo:[0,1] neg_hi:[0,1]
	v_sub_f32_e32 v94, v94, v68
	v_sub_f32_e32 v95, v95, v68
	v_pk_add_f32 v[96:97], v[96:97], v[68:69] op_sel_hi:[1,0] neg_lo:[0,1] neg_hi:[0,1]
	v_pk_add_f32 v[98:99], v[98:99], v[68:69] op_sel_hi:[1,0] neg_lo:[0,1] neg_hi:[0,1]
	v_pk_add_f32 v[100:101], v[100:101], v[68:69] op_sel_hi:[1,0] neg_lo:[0,1] neg_hi:[0,1]
	v_pk_add_f32 v[102:103], v[102:103], v[68:69] op_sel_hi:[1,0] neg_lo:[0,1] neg_hi:[0,1]
	v_pk_add_f32 v[104:105], v[104:105], v[68:69] op_sel_hi:[1,0] neg_lo:[0,1] neg_hi:[0,1]
	v_pk_add_f32 v[106:107], v[106:107], v[68:69] op_sel_hi:[1,0] neg_lo:[0,1] neg_hi:[0,1]
	v_pk_add_f32 v[108:109], v[108:109], v[68:69] op_sel_hi:[1,0] neg_lo:[0,1] neg_hi:[0,1]
	v_mul_f32_e32 v195, v195, v66
	v_mov_b32_e32 v196, v65
	v_cmp_lt_f32_e32 vcc, s14, v196
	s_nop 1
	v_cndmask_b32_e64 v232, 0, -v196, vcc
	v_mov_b32_e32 v233, v232
	v_mov_b32_e32 v234, v232
	v_mov_b32_e32 v235, v232
	v_mov_b32_e32 v236, v232
	v_mov_b32_e32 v237, v232
	v_mov_b32_e32 v238, v232
	v_mov_b32_e32 v239, v232
	v_mov_b32_e32 v240, v232
	v_mov_b32_e32 v241, v232
	v_mov_b32_e32 v242, v232
	v_mov_b32_e32 v243, v232
	v_mov_b32_e32 v244, v232
	v_mov_b32_e32 v245, v232
	v_mov_b32_e32 v246, v232
	v_mov_b32_e32 v247, v232
	s_branch .LBB0_780
